# v11 + attention step 0: twelve K-fragment reads issued up front, counted lgkmcnt waits
# speedup vs baseline: 1.0032x; 1.0032x over previous
.LBB0_561:
	s_or_b64 exec, exec, s[0:1]
	s_waitcnt vmcnt(5) lgkmcnt(0)
	s_barrier
	ds_read_b128 v[36:39], v179
	ds_read_b128 v[40:43], v179 offset:512
	ds_read_b128 v[44:47], v179 offset:2048
	ds_read_b128 v[48:51], v179 offset:2560
	ds_read_b128 v[52:55], v179 offset:4096
	ds_read_b128 v[56:59], v179 offset:4608
	ds_read_b128 v[60:63], v179 offset:6144
	ds_read_b128 v[64:67], v179 offset:6656
	ds_read_b128 v[68:71], v179 offset:8192
	ds_read_b128 v[72:75], v179 offset:8704
	ds_read_b128 v[76:79], v179 offset:10240
	ds_read_b128 v[80:83], v179 offset:10752
	s_cmp_lg_u32 s62, 0
	s_cselect_b64 s[0:1], -1, 0
	s_and_b64 vcc, exec, s[0:1]
	s_waitcnt lgkmcnt(11)
	v_mfma_f32_32x32x16_bf16 v[16:31], v[36:39], v[116:119], 0
	s_waitcnt lgkmcnt(10)
	v_mfma_f32_32x32x16_bf16 v[0:15], v[40:43], v[116:119], 0
	s_waitcnt lgkmcnt(9)
	v_mfma_f32_32x32x16_bf16 v[16:31], v[44:47], v[112:115], v[16:31]
	s_waitcnt lgkmcnt(8)
	v_mfma_f32_32x32x16_bf16 v[0:15], v[48:51], v[112:115], v[0:15]
	s_waitcnt lgkmcnt(7)
	v_mfma_f32_32x32x16_bf16 v[16:31], v[52:55], v[104:107], v[16:31]
	s_waitcnt lgkmcnt(6)
	v_mfma_f32_32x32x16_bf16 v[0:15], v[56:59], v[104:107], v[0:15]
	s_waitcnt lgkmcnt(5)
	v_mfma_f32_32x32x16_bf16 v[16:31], v[60:63], v[96:99], v[16:31]
	s_waitcnt lgkmcnt(4)
	v_mfma_f32_32x32x16_bf16 v[0:15], v[64:67], v[96:99], v[0:15]
	s_waitcnt lgkmcnt(3)
	v_mfma_f32_32x32x16_bf16 v[16:31], v[68:71], v[108:111], v[16:31]
	s_waitcnt lgkmcnt(2)
	v_mfma_f32_32x32x16_bf16 v[0:15], v[72:75], v[108:111], v[0:15]
	s_waitcnt lgkmcnt(1)
	v_mfma_f32_32x32x16_bf16 v[16:31], v[76:79], v[100:103], v[16:31]
	s_waitcnt lgkmcnt(0)
	v_mfma_f32_32x32x16_bf16 v[0:15], v[80:83], v[100:103], v[0:15]
	s_cbranch_vccnz .LBB0_563
	v_readlane_b32 s48, v246, 61
	v_readlane_b32 s49, v246, 62
	s_nop 5
	v_cndmask_b32_e64 v32, v16, v218, s[48:49]
	v_readlane_b32 s48, v246, 63
	v_readlane_b32 s49, v245, 0
	s_nop 1
	v_cndmask_b32_e64 v0, v0, v218, s[48:49]
	v_readlane_b32 s48, v245, 1
	v_readlane_b32 s49, v245, 2
	s_nop 1
	v_cndmask_b32_e64 v17, v218, v17, s[48:49]
	v_cndmask_b32_e64 v16, v32, v16, s[48:49]
	v_readlane_b32 s48, v245, 3
	v_readlane_b32 s49, v245, 4
	s_nop 1
	v_cndmask_b32_e64 v1, v1, v218, s[48:49]
	v_readlane_b32 s48, v245, 5
	v_readlane_b32 s49, v245, 6
	s_nop 1
	v_cndmask_b32_e64 v18, v18, v218, s[48:49]
	v_readlane_b32 s48, v245, 7
	v_readlane_b32 s49, v245, 8
	s_nop 1
	v_cndmask_b32_e64 v2, v2, v218, s[48:49]
	v_readlane_b32 s48, v245, 9
	v_readlane_b32 s49, v245, 10
	s_nop 1
	v_cndmask_b32_e64 v19, v19, v218, s[48:49]
	v_readlane_b32 s48, v245, 11
	v_readlane_b32 s49, v245, 12
	s_nop 1
	v_cndmask_b32_e64 v3, v3, v218, s[48:49]
	v_readlane_b32 s48, v245, 13
	v_readlane_b32 s49, v245, 14
	s_nop 1
	v_cndmask_b32_e64 v20, v20, v218, s[48:49]
	v_readlane_b32 s48, v245, 15
	v_readlane_b32 s49, v245, 16
	s_nop 1
	v_cndmask_b32_e64 v4, v4, v218, s[48:49]
	v_readlane_b32 s48, v245, 17
	v_readlane_b32 s49, v245, 18
	s_nop 1
	v_cndmask_b32_e64 v21, v21, v218, s[48:49]
	v_readlane_b32 s48, v245, 19
	v_readlane_b32 s49, v245, 20
	s_nop 1
	v_cndmask_b32_e64 v5, v5, v218, s[48:49]
	v_readlane_b32 s48, v245, 21
	v_readlane_b32 s49, v245, 22
	s_nop 1
	v_cndmask_b32_e64 v22, v22, v218, s[48:49]
	v_readlane_b32 s48, v245, 23
	v_readlane_b32 s49, v245, 24
	s_nop 1
	v_cndmask_b32_e64 v6, v6, v218, s[48:49]
	v_readlane_b32 s48, v245, 25
	v_readlane_b32 s49, v245, 26
	s_nop 1
	v_cndmask_b32_e64 v23, v23, v218, s[48:49]
	v_readlane_b32 s48, v245, 27
	v_readlane_b32 s49, v245, 28
	s_nop 1
	v_cndmask_b32_e64 v7, v7, v218, s[48:49]
	v_readlane_b32 s48, v245, 29
	v_readlane_b32 s49, v245, 30
	s_nop 1
	v_cndmask_b32_e64 v24, v24, v218, s[48:49]
	v_readlane_b32 s48, v245, 31
	v_readlane_b32 s49, v245, 32
	s_nop 1
	v_cndmask_b32_e64 v8, v8, v218, s[48:49]
	v_readlane_b32 s48, v245, 33
	v_readlane_b32 s49, v245, 34
	s_nop 1
	v_cndmask_b32_e64 v25, v25, v218, s[48:49]
	v_readlane_b32 s48, v245, 35
	v_readlane_b32 s49, v245, 36
	s_nop 1
	v_cndmask_b32_e64 v9, v9, v218, s[48:49]
	v_readlane_b32 s48, v245, 37
	v_readlane_b32 s49, v245, 38
	s_nop 1
	v_cndmask_b32_e64 v26, v26, v218, s[48:49]
	v_readlane_b32 s48, v245, 39
	v_readlane_b32 s49, v245, 40
	s_nop 1
	v_cndmask_b32_e64 v10, v10, v218, s[48:49]
	v_readlane_b32 s48, v245, 41
	v_readlane_b32 s49, v245, 42
	s_nop 1
	v_cndmask_b32_e64 v27, v27, v218, s[48:49]
	v_readlane_b32 s48, v245, 43
	v_readlane_b32 s49, v245, 44
	s_nop 1
	v_cndmask_b32_e64 v11, v11, v218, s[48:49]
	v_readlane_b32 s48, v245, 45
	v_readlane_b32 s49, v245, 46
	s_nop 1
	v_cndmask_b32_e64 v28, v28, v218, s[48:49]
	v_readlane_b32 s48, v245, 47
	v_readlane_b32 s49, v245, 48
	s_nop 1
	v_cndmask_b32_e64 v12, v12, v218, s[48:49]
	v_readlane_b32 s48, v245, 49
	v_readlane_b32 s49, v245, 50
	s_nop 1
	v_cndmask_b32_e64 v29, v29, v218, s[48:49]
	v_readlane_b32 s48, v245, 51
	v_readlane_b32 s49, v245, 52
	s_nop 1
	v_cndmask_b32_e64 v13, v13, v218, s[48:49]
	v_readlane_b32 s48, v245, 53
	v_readlane_b32 s49, v245, 54
	s_nop 1
	v_cndmask_b32_e64 v30, v30, v218, s[48:49]
	v_readlane_b32 s48, v245, 55
	v_readlane_b32 s49, v245, 56
	s_nop 1
	v_cndmask_b32_e64 v14, v14, v218, s[48:49]
	v_readlane_b32 s48, v245, 57
	v_readlane_b32 s49, v245, 58
	s_nop 1
	v_cndmask_b32_e64 v31, v31, v218, s[48:49]
	v_readlane_b32 s48, v245, 59
	v_readlane_b32 s49, v245, 60
	s_nop 1
	v_cndmask_b32_e64 v15, v15, v218, s[48:49]
